# V10 + static s_setprio 1 for waves 4-7 during the two attention phases
# baseline (speedup 1.0000x reference)
.LBB0_94:
	v_writelane_b32 v250, s2, 27
	s_andn2_b64 vcc, exec, s[0:1]
	s_nop 0
	v_writelane_b32 v250, s3, 28
	s_cbranch_vccnz .LBB0_175
	v_mov_b32_e32 v0, v144
	s_nop 0
	v_readfirstlane_b32 s2, v0
	v_cmp_eq_u32_e64 s[64:65], 0, v0
	s_barrier
	s_cmp_lt_u32 s2, 0x100
	s_cbranch_scc1 .Lmy_p6prio_skip
	s_setprio 1
.Lmy_p6prio_skip:
	s_and_saveexec_b64 s[0:1], s[64:65]
	s_cbranch_execz .LBB0_99
	s_mov_b64 s[14:15], exec
	s_waitcnt vmcnt(0) lgkmcnt(0)
	v_mbcnt_lo_u32_b32 v2, s14, 0
	v_mbcnt_hi_u32_b32 v2, s15, v2
	v_cmp_eq_u32_e32 vcc, 0, v2
	s_and_saveexec_b64 s[6:7], vcc
	s_cbranch_execz .LBB0_98
	s_bcnt1_i32_b64 s3, s[14:15]
	v_readlane_b32 s8, v252, 41
	v_mov_b32_e32 v3, s3
	v_readlane_b32 s9, v252, 42
	s_nop 4
	global_atomic_add v3, v1, v3, s[8:9] sc0

.LBB0_175:
	s_setprio 0
	s_branch .LBB0_381

.LBB0_548:
	s_andn2_b64 vcc, exec, s[0:1]
	v_readlane_b32 s29, v251, 30
	s_cbranch_vccnz .LBB0_810
	v_mov_b32_e32 v154, v144
	s_waitcnt vmcnt(0) lgkmcnt(0)
	v_cmp_eq_u32_e64 s[4:5], 0, v154
	v_readfirstlane_b32 s3, v154
	s_barrier
	s_cmp_lt_u32 s3, 0x100
	s_cbranch_scc1 .Lmy_p2prio_skip
	s_setprio 1
.Lmy_p2prio_skip:
	v_writelane_b32 v250, s4, 23
	s_nop 1
	v_writelane_b32 v250, s5, 24
	s_and_saveexec_b64 s[0:1], s[4:5]
	s_cbranch_execz .LBB0_553
	s_mov_b64 s[14:15], exec
	v_mbcnt_lo_u32_b32 v0, s14, 0
	v_mbcnt_hi_u32_b32 v0, s15, v0
	v_cmp_eq_u32_e32 vcc, 0, v0
	s_and_saveexec_b64 s[6:7], vcc
	s_cbranch_execz .LBB0_552
	s_bcnt1_i32_b64 s2, s[14:15]
	v_mov_b32_e32 v2, s2
	global_atomic_add v2, v1, v2, s[26:27] sc0

.LBB0_810:
	s_setprio 0
	s_mov_b64 s[4:5], 0
